# attention steady steps: waves 4-7 run the 3 post-barrier PV MFMAs + 6 exps before their closing barrier (work-preserving stagger of the halves)
# speedup vs baseline: 1.0014x; 1.0014x over previous
.LBB0_974:
	v_add_u32_e32 v94, s44, v241
	v_add_u32_e32 v102, s40, v228
	ds_read_b128 v[82:85], v94
	ds_read_b128 v[198:201], v94 offset:512
	ds_read_b128 v[202:205], v94 offset:2048
	ds_read_b128 v[194:197], v94 offset:2560
	s_waitcnt lgkmcnt(10)
	v_mfma_f32_32x32x16_bf16 v[50:65], v[150:153], v[106:109], v[50:65]
	v_exp_f32_e32 v130, v130
	v_exp_f32_e32 v131, v131
	v_exp_f32_e32 v132, v132
	ds_read_b128 v[190:193], v94 offset:4096
	ds_read_b128 v[186:189], v94 offset:4608
	ds_read_b128 v[182:185], v94 offset:6144
	ds_read_b128 v[178:181], v94 offset:6656
	ds_read_b64_tr_b16 v[98:99],v102 offset:3072
	ds_read_b64_tr_b16 v[100:101],v102 offset:3584
	ds_read_b64_tr_b16 v[94:95],v102 offset:2048
	ds_read_b64_tr_b16 v[96:97],v102 offset:2560
	s_waitcnt lgkmcnt(15)
	v_mfma_f32_32x32x16_bf16 v[34:49], v[150:153], v[110:113], v[34:49]
	v_exp_f32_e32 v133, v133
	v_exp_f32_e32 v134, v134
	v_exp_f32_e32 v135, v135
	s_waitcnt lgkmcnt(14)
	v_mfma_f32_32x32x16_bf16 v[50:65], v[146:149], v[86:89], v[50:65]
	v_exp_f32_e32 v136, v136
	v_exp_f32_e32 v137, v137
	v_exp_f32_e32 v138, v138
	ds_read_b64_tr_b16 v[86:87],v102 offset:0
	ds_read_b64_tr_b16 v[88:89],v102 offset:512
	s_waitcnt lgkmcnt(14)
	v_mfma_f32_32x32x16_bf16 v[34:49], v[146:149], v[90:93], v[34:49]
	v_exp_f32_e32 v139, v139
	v_exp_f32_e32 v140, v140
	v_exp_f32_e32 v141, v141
	ds_read_b64_tr_b16 v[90:91],v102 offset:1024
	ds_read_b64_tr_b16 v[92:93],v102 offset:1536
	s_waitcnt lgkmcnt(6)
	v_mfma_f32_32x32x16_bf16 v[18:33], v[146:149], v[98:101], v[18:33]
	v_exp_f32_e32 v142, v142
	v_exp_f32_e32 v143, v143
	v_exp_f32_e32 v144, v144
	ds_read_b64_tr_b16 v[98:99],v102 offset:7168
	ds_read_b64_tr_b16 v[100:101],v102 offset:7680
	s_waitcnt lgkmcnt(6)
	v_mfma_f32_32x32x16_bf16 v[18:33], v[150:153], v[94:97], v[18:33]
	v_exp_f32_e32 v145, v145
	v_exp_f32_e32 v114, v114
	v_exp_f32_e32 v115, v115
	ds_read_b64_tr_b16 v[94:95],v102 offset:6144
	ds_read_b64_tr_b16 v[96:97],v102 offset:6656
	s_waitcnt lgkmcnt(6)
	v_mfma_f32_32x32x16_bf16 v[18:33], v[158:161], v[86:89], v[18:33]
	v_exp_f32_e32 v116, v116
	v_exp_f32_e32 v117, v117
	v_exp_f32_e32 v118, v118
	ds_read_b64_tr_b16 v[86:87],v102 offset:4096
	ds_read_b64_tr_b16 v[88:89],v102 offset:4608
	s_waitcnt lgkmcnt(6)
	v_mfma_f32_32x32x16_bf16 v[18:33], v[154:157], v[90:93], v[18:33]
	v_exp_f32_e32 v119, v119
	v_exp_f32_e32 v120, v120
	v_exp_f32_e32 v121, v121
	ds_read_b64_tr_b16 v[90:91],v102 offset:5120
	ds_read_b64_tr_b16 v[92:93],v102 offset:5632
	s_waitcnt lgkmcnt(6)
	v_mfma_f32_32x32x16_bf16 v[2:17], v[146:149], v[98:101], v[2:17]
	v_exp_f32_e32 v122, v122
	v_exp_f32_e32 v123, v123
	s_cmp_lt_u32 s83, 0x1000
	s_cbranch_scc1 .Lstg_lead_0
	s_waitcnt lgkmcnt(0)
	s_andn2_b64 vcc, exec, s[2:3]
	v_add_u32_e32 v229, s94, v243
	v_mfma_f32_32x32x16_bf16 v[2:17], v[150:153], v[94:97], v[2:17]
	v_exp_f32_e32 v124, v124
	v_exp_f32_e32 v125, v125
	v_mfma_f32_32x32x16_bf16 v[2:17], v[158:161], v[86:89], v[2:17]
	v_exp_f32_e32 v126, v126
	v_exp_f32_e32 v127, v127
	v_mfma_f32_32x32x16_bf16 v[2:17], v[154:157], v[90:93], v[2:17]
	v_exp_f32_e32 v128, v128
	v_exp_f32_e32 v129, v129
	s_waitcnt vmcnt(3)
	s_barrier
	s_branch .Lstg_join_0
.Lstg_lead_0:
	s_waitcnt vmcnt(3) lgkmcnt(0)
	s_barrier
	s_andn2_b64 vcc, exec, s[2:3]
	v_add_u32_e32 v229, s94, v243
	v_mfma_f32_32x32x16_bf16 v[2:17], v[150:153], v[94:97], v[2:17]
	v_exp_f32_e32 v124, v124
	v_exp_f32_e32 v125, v125
	v_mfma_f32_32x32x16_bf16 v[2:17], v[158:161], v[86:89], v[2:17]
	v_exp_f32_e32 v126, v126
	v_exp_f32_e32 v127, v127
	v_mfma_f32_32x32x16_bf16 v[2:17], v[154:157], v[90:93], v[2:17]
	v_exp_f32_e32 v128, v128
	v_exp_f32_e32 v129, v129
.Lstg_join_0:
	s_cbranch_vccnz .LBB0_976
	s_waitcnt lgkmcnt(0)
	ds_read_b128 v[86:89], v229 offset:96
	ds_read_b128 v[90:93], v229 offset:64
	ds_read_b128 v[94:97], v229 offset:32
	ds_read_b128 v[98:101], v229
	s_waitcnt lgkmcnt(3)
	v_pk_mul_f32 v[62:63], v[62:63], v[86:87]
	s_waitcnt lgkmcnt(2)
	v_pk_mul_f32 v[58:59], v[58:59], v[90:91]
	s_waitcnt lgkmcnt(1)
	v_pk_mul_f32 v[54:55], v[54:55], v[94:95]
	v_pk_mul_f32 v[64:65], v[64:65], v[88:89]
	v_pk_mul_f32 v[60:61], v[60:61], v[92:93]
	v_pk_mul_f32 v[56:57], v[56:57], v[96:97]
	s_waitcnt lgkmcnt(0)
	v_pk_mul_f32 v[52:53], v[52:53], v[100:101]
	v_pk_mul_f32 v[50:51], v[50:51], v[98:99]
	v_pk_mul_f32 v[46:47], v[46:47], v[86:87]
	v_pk_mul_f32 v[42:43], v[42:43], v[90:91]
	v_pk_mul_f32 v[38:39], v[38:39], v[94:95]
	v_pk_mul_f32 v[48:49], v[48:49], v[88:89]
	v_pk_mul_f32 v[44:45], v[44:45], v[92:93]
	v_pk_mul_f32 v[40:41], v[40:41], v[96:97]
	v_pk_mul_f32 v[36:37], v[36:37], v[100:101]
	v_pk_mul_f32 v[34:35], v[34:35], v[98:99]
	v_pk_mul_f32 v[30:31], v[30:31], v[86:87]
	v_pk_mul_f32 v[26:27], v[26:27], v[90:91]
	v_pk_mul_f32 v[22:23], v[22:23], v[94:95]
	v_pk_mul_f32 v[32:33], v[32:33], v[88:89]
	v_pk_mul_f32 v[28:29], v[28:29], v[92:93]
	v_pk_mul_f32 v[24:25], v[24:25], v[96:97]
	v_pk_mul_f32 v[20:21], v[20:21], v[100:101]
	v_pk_mul_f32 v[18:19], v[18:19], v[98:99]
	v_pk_mul_f32 v[14:15], v[14:15], v[86:87]
	v_pk_mul_f32 v[10:11], v[10:11], v[90:91]
	v_pk_mul_f32 v[6:7], v[6:7], v[94:95]
	v_pk_mul_f32 v[16:17], v[16:17], v[88:89]
	v_pk_mul_f32 v[12:13], v[12:13], v[92:93]
	v_pk_mul_f32 v[8:9], v[8:9], v[96:97]
	v_pk_mul_f32 v[4:5], v[4:5], v[100:101]
	v_pk_mul_f32 v[2:3], v[2:3], v[98:99]

.LBB0_977:
	v_add_u32_e32 v126, s40, v241
	v_add_u32_e32 v130, s45, v228
	ds_read_b128 v[206:209], v126
	ds_read_b128 v[202:205], v126 offset:512
	ds_read_b128 v[198:201], v126 offset:2048
	ds_read_b128 v[194:197], v126 offset:2560
	s_waitcnt lgkmcnt(10)
	v_mfma_f32_32x32x16_bf16 v[50:65], v[150:153], v[138:141], v[50:65]
	v_exp_f32_e32 v98, v98
	v_exp_f32_e32 v99, v99
	v_exp_f32_e32 v100, v100
	ds_read_b128 v[190:193], v126 offset:4096
	ds_read_b128 v[186:189], v126 offset:4608
	ds_read_b128 v[182:185], v126 offset:6144
	ds_read_b128 v[178:181], v126 offset:6656
	ds_read_b64_tr_b16 v[126:127],v130 offset:3072
	ds_read_b64_tr_b16 v[128:129],v130 offset:3584
	s_waitcnt lgkmcnt(14)
	v_mfma_f32_32x32x16_bf16 v[34:49], v[150:153], v[114:117], v[34:49]
	v_exp_f32_e32 v101, v101
	v_exp_f32_e32 v102, v102
	v_exp_f32_e32 v103, v103
	ds_read_b64_tr_b16 v[114:115],v130 offset:0
	ds_read_b64_tr_b16 v[116:117],v130 offset:512
	s_waitcnt lgkmcnt(14)
	v_mfma_f32_32x32x16_bf16 v[50:65], v[146:149], v[118:121], v[50:65]
	v_exp_f32_e32 v104, v104
	v_exp_f32_e32 v105, v105
	v_exp_f32_e32 v106, v106
	ds_read_b64_tr_b16 v[118:119],v130 offset:1024
	ds_read_b64_tr_b16 v[120:121],v130 offset:1536
	s_waitcnt lgkmcnt(14)
	v_mfma_f32_32x32x16_bf16 v[34:49], v[146:149], v[122:125], v[34:49]
	v_exp_f32_e32 v107, v107
	v_exp_f32_e32 v108, v108
	v_exp_f32_e32 v109, v109
	ds_read_b64_tr_b16 v[122:123],v130 offset:2048
	ds_read_b64_tr_b16 v[124:125],v130 offset:2560
	s_waitcnt lgkmcnt(6)
	v_mfma_f32_32x32x16_bf16 v[18:33], v[146:149], v[126:129], v[18:33]
	v_exp_f32_e32 v110, v110
	v_exp_f32_e32 v111, v111
	v_exp_f32_e32 v112, v112
	ds_read_b64_tr_b16 v[126:127],v130 offset:7168
	ds_read_b64_tr_b16 v[128:129],v130 offset:7680
	s_waitcnt lgkmcnt(6)
	v_mfma_f32_32x32x16_bf16 v[18:33], v[158:161], v[114:117], v[18:33]
	v_exp_f32_e32 v113, v113
	v_exp_f32_e32 v82, v82
	v_exp_f32_e32 v83, v83
	ds_read_b64_tr_b16 v[114:115],v130 offset:4096
	ds_read_b64_tr_b16 v[116:117],v130 offset:4608
	s_waitcnt lgkmcnt(6)
	v_mfma_f32_32x32x16_bf16 v[18:33], v[154:157], v[118:121], v[18:33]
	v_exp_f32_e32 v84, v84
	v_exp_f32_e32 v85, v85
	v_exp_f32_e32 v86, v86
	ds_read_b64_tr_b16 v[118:119],v130 offset:5120
	ds_read_b64_tr_b16 v[120:121],v130 offset:5632
	s_waitcnt lgkmcnt(6)
	v_mfma_f32_32x32x16_bf16 v[18:33], v[150:153], v[122:125], v[18:33]
	v_exp_f32_e32 v87, v87
	v_exp_f32_e32 v88, v88
	v_exp_f32_e32 v89, v89
	ds_read_b64_tr_b16 v[122:123],v130 offset:6144
	ds_read_b64_tr_b16 v[124:125],v130 offset:6656
	s_waitcnt lgkmcnt(6)
	v_mfma_f32_32x32x16_bf16 v[2:17], v[146:149], v[126:129], v[2:17]
	v_exp_f32_e32 v90, v90
	v_exp_f32_e32 v91, v91
	s_cmp_lt_u32 s83, 0x1000
	s_cbranch_scc1 .Lstg_lead_1
	s_waitcnt lgkmcnt(0)
	s_andn2_b64 vcc, exec, s[2:3]
	v_mfma_f32_32x32x16_bf16 v[2:17], v[158:161], v[114:117], v[2:17]
	v_exp_f32_e32 v92, v92
	v_exp_f32_e32 v93, v93
	v_mfma_f32_32x32x16_bf16 v[2:17], v[154:157], v[118:121], v[2:17]
	v_exp_f32_e32 v94, v94
	v_exp_f32_e32 v95, v95
	v_mfma_f32_32x32x16_bf16 v[2:17], v[150:153], v[122:125], v[2:17]
	v_exp_f32_e32 v96, v96
	v_exp_f32_e32 v97, v97
	s_waitcnt vmcnt(3)
	s_barrier
	s_branch .Lstg_join_1
.Lstg_lead_1:
	s_waitcnt vmcnt(3) lgkmcnt(0)
	s_barrier
	s_andn2_b64 vcc, exec, s[2:3]
	v_mfma_f32_32x32x16_bf16 v[2:17], v[158:161], v[114:117], v[2:17]
	v_exp_f32_e32 v92, v92
	v_exp_f32_e32 v93, v93
	v_mfma_f32_32x32x16_bf16 v[2:17], v[154:157], v[118:121], v[2:17]
	v_exp_f32_e32 v94, v94
	v_exp_f32_e32 v95, v95
	v_mfma_f32_32x32x16_bf16 v[2:17], v[150:153], v[122:125], v[2:17]
	v_exp_f32_e32 v96, v96
	v_exp_f32_e32 v97, v97
.Lstg_join_1:
	s_cbranch_vccnz .LBB0_979
	s_waitcnt lgkmcnt(0)
	ds_read_b128 v[114:117], v229 offset:96
	ds_read_b128 v[118:121], v229 offset:64
	ds_read_b128 v[122:125], v229 offset:32
	ds_read_b128 v[126:129], v229
	s_waitcnt lgkmcnt(3)
	v_pk_mul_f32 v[62:63], v[62:63], v[114:115]
	s_waitcnt lgkmcnt(2)
	v_pk_mul_f32 v[58:59], v[58:59], v[118:119]
	s_waitcnt lgkmcnt(1)
	v_pk_mul_f32 v[54:55], v[54:55], v[122:123]
	v_pk_mul_f32 v[64:65], v[64:65], v[116:117]
	v_pk_mul_f32 v[60:61], v[60:61], v[120:121]
	v_pk_mul_f32 v[56:57], v[56:57], v[124:125]
	s_waitcnt lgkmcnt(0)
	v_pk_mul_f32 v[52:53], v[52:53], v[128:129]
	v_pk_mul_f32 v[50:51], v[50:51], v[126:127]
	v_pk_mul_f32 v[46:47], v[46:47], v[114:115]
	v_pk_mul_f32 v[42:43], v[42:43], v[118:119]
	v_pk_mul_f32 v[38:39], v[38:39], v[122:123]
	v_pk_mul_f32 v[48:49], v[48:49], v[116:117]
	v_pk_mul_f32 v[44:45], v[44:45], v[120:121]
	v_pk_mul_f32 v[40:41], v[40:41], v[124:125]
	v_pk_mul_f32 v[36:37], v[36:37], v[128:129]
	v_pk_mul_f32 v[34:35], v[34:35], v[126:127]
	v_pk_mul_f32 v[30:31], v[30:31], v[114:115]
	v_pk_mul_f32 v[26:27], v[26:27], v[118:119]
	v_pk_mul_f32 v[22:23], v[22:23], v[122:123]
	v_pk_mul_f32 v[32:33], v[32:33], v[116:117]
	v_pk_mul_f32 v[28:29], v[28:29], v[120:121]
	v_pk_mul_f32 v[24:25], v[24:25], v[124:125]
	v_pk_mul_f32 v[20:21], v[20:21], v[128:129]
	v_pk_mul_f32 v[18:19], v[18:19], v[126:127]
	v_pk_mul_f32 v[14:15], v[14:15], v[114:115]
	v_pk_mul_f32 v[10:11], v[10:11], v[118:119]
	v_pk_mul_f32 v[6:7], v[6:7], v[122:123]
	v_pk_mul_f32 v[16:17], v[16:17], v[116:117]
	v_pk_mul_f32 v[12:13], v[12:13], v[120:121]
	v_pk_mul_f32 v[8:9], v[8:9], v[124:125]
	v_pk_mul_f32 v[4:5], v[4:5], v[128:129]
	v_pk_mul_f32 v[2:3], v[2:3], v[126:127]

.LBB0_1080:
	v_add_u32_e32 v94, s43, v241
	v_add_u32_e32 v102, s40, v228
	ds_read_b128 v[82:85], v94
	ds_read_b128 v[198:201], v94 offset:512
	ds_read_b128 v[202:205], v94 offset:2048
	ds_read_b128 v[194:197], v94 offset:2560
	s_waitcnt lgkmcnt(10)
	v_mfma_f32_32x32x16_bf16 v[50:65], v[158:161], v[106:109], v[50:65]
	v_exp_f32_e32 v130, v130
	v_exp_f32_e32 v131, v131
	v_exp_f32_e32 v132, v132
	ds_read_b128 v[190:193], v94 offset:4096
	ds_read_b128 v[186:189], v94 offset:4608
	ds_read_b128 v[182:185], v94 offset:6144
	ds_read_b128 v[178:181], v94 offset:6656
	ds_read_b64_tr_b16 v[98:99],v102 offset:3072
	ds_read_b64_tr_b16 v[100:101],v102 offset:3584
	ds_read_b64_tr_b16 v[94:95],v102 offset:2048
	ds_read_b64_tr_b16 v[96:97],v102 offset:2560
	s_waitcnt lgkmcnt(15)
	v_mfma_f32_32x32x16_bf16 v[34:49], v[158:161], v[110:113], v[34:49]
	v_exp_f32_e32 v133, v133
	v_exp_f32_e32 v134, v134
	v_exp_f32_e32 v135, v135
	s_waitcnt lgkmcnt(14)
	v_mfma_f32_32x32x16_bf16 v[50:65], v[154:157], v[86:89], v[50:65]
	v_exp_f32_e32 v136, v136
	v_exp_f32_e32 v137, v137
	v_exp_f32_e32 v138, v138
	ds_read_b64_tr_b16 v[86:87],v102 offset:0
	ds_read_b64_tr_b16 v[88:89],v102 offset:512
	s_waitcnt lgkmcnt(14)
	v_mfma_f32_32x32x16_bf16 v[34:49], v[154:157], v[90:93], v[34:49]
	v_exp_f32_e32 v139, v139
	v_exp_f32_e32 v140, v140
	v_exp_f32_e32 v141, v141
	ds_read_b64_tr_b16 v[90:91],v102 offset:1024
	ds_read_b64_tr_b16 v[92:93],v102 offset:1536
	s_waitcnt lgkmcnt(6)
	v_mfma_f32_32x32x16_bf16 v[18:33], v[154:157], v[98:101], v[18:33]
	v_exp_f32_e32 v142, v142
	v_exp_f32_e32 v143, v143
	v_exp_f32_e32 v144, v144
	ds_read_b64_tr_b16 v[98:99],v102 offset:7168
	ds_read_b64_tr_b16 v[100:101],v102 offset:7680
	s_waitcnt lgkmcnt(6)
	v_mfma_f32_32x32x16_bf16 v[18:33], v[158:161], v[94:97], v[18:33]
	v_exp_f32_e32 v145, v145
	v_exp_f32_e32 v114, v114
	v_exp_f32_e32 v115, v115
	ds_read_b64_tr_b16 v[94:95],v102 offset:6144
	ds_read_b64_tr_b16 v[96:97],v102 offset:6656
	s_waitcnt lgkmcnt(6)
	v_mfma_f32_32x32x16_bf16 v[18:33], v[166:169], v[86:89], v[18:33]
	v_exp_f32_e32 v116, v116
	v_exp_f32_e32 v117, v117
	v_exp_f32_e32 v118, v118
	ds_read_b64_tr_b16 v[86:87],v102 offset:4096
	ds_read_b64_tr_b16 v[88:89],v102 offset:4608
	s_waitcnt lgkmcnt(6)
	v_mfma_f32_32x32x16_bf16 v[18:33], v[162:165], v[90:93], v[18:33]
	v_exp_f32_e32 v119, v119
	v_exp_f32_e32 v120, v120
	v_exp_f32_e32 v121, v121
	ds_read_b64_tr_b16 v[90:91],v102 offset:5120
	ds_read_b64_tr_b16 v[92:93],v102 offset:5632
	s_waitcnt lgkmcnt(6)
	v_mfma_f32_32x32x16_bf16 v[2:17], v[154:157], v[98:101], v[2:17]
	v_exp_f32_e32 v122, v122
	v_exp_f32_e32 v123, v123
	s_cmp_lt_u32 s44, 0x1000
	s_cbranch_scc1 .Lstg_lead_2
	s_waitcnt lgkmcnt(0)
	s_andn2_b64 vcc, exec, s[2:3]
	v_add_u32_e32 v229, s39, v243
	v_mfma_f32_32x32x16_bf16 v[2:17], v[158:161], v[94:97], v[2:17]
	v_exp_f32_e32 v124, v124
	v_exp_f32_e32 v125, v125
	v_mfma_f32_32x32x16_bf16 v[2:17], v[166:169], v[86:89], v[2:17]
	v_exp_f32_e32 v126, v126
	v_exp_f32_e32 v127, v127
	v_mfma_f32_32x32x16_bf16 v[2:17], v[162:165], v[90:93], v[2:17]
	v_exp_f32_e32 v128, v128
	v_exp_f32_e32 v129, v129
	s_waitcnt vmcnt(3)
	s_barrier
	s_branch .Lstg_join_2
.Lstg_lead_2:
	s_waitcnt vmcnt(3) lgkmcnt(0)
	s_barrier
	s_andn2_b64 vcc, exec, s[2:3]
	v_add_u32_e32 v229, s39, v243
	v_mfma_f32_32x32x16_bf16 v[2:17], v[158:161], v[94:97], v[2:17]
	v_exp_f32_e32 v124, v124
	v_exp_f32_e32 v125, v125
	v_mfma_f32_32x32x16_bf16 v[2:17], v[166:169], v[86:89], v[2:17]
	v_exp_f32_e32 v126, v126
	v_exp_f32_e32 v127, v127
	v_mfma_f32_32x32x16_bf16 v[2:17], v[162:165], v[90:93], v[2:17]
	v_exp_f32_e32 v128, v128
	v_exp_f32_e32 v129, v129

.LBB0_1083:
	v_add_u32_e32 v126, s40, v241
	v_add_u32_e32 v130, s47, v228
	ds_read_b128 v[206:209], v126
	ds_read_b128 v[198:201], v126 offset:512
	ds_read_b128 v[202:205], v126 offset:2048
	ds_read_b128 v[194:197], v126 offset:2560
	s_waitcnt lgkmcnt(10)
	v_mfma_f32_32x32x16_bf16 v[50:65], v[158:161], v[138:141], v[50:65]
	v_exp_f32_e32 v98, v98
	v_exp_f32_e32 v99, v99
	v_exp_f32_e32 v100, v100
	ds_read_b128 v[190:193], v126 offset:4096
	ds_read_b128 v[186:189], v126 offset:4608
	ds_read_b128 v[182:185], v126 offset:6144
	ds_read_b128 v[178:181], v126 offset:6656
	ds_read_b64_tr_b16 v[126:127],v130 offset:3072
	ds_read_b64_tr_b16 v[128:129],v130 offset:3584
	s_waitcnt lgkmcnt(14)
	v_mfma_f32_32x32x16_bf16 v[34:49], v[158:161], v[114:117], v[34:49]
	v_exp_f32_e32 v101, v101
	v_exp_f32_e32 v102, v102
	v_exp_f32_e32 v103, v103
	ds_read_b64_tr_b16 v[114:115],v130 offset:0
	ds_read_b64_tr_b16 v[116:117],v130 offset:512
	s_waitcnt lgkmcnt(14)
	v_mfma_f32_32x32x16_bf16 v[50:65], v[154:157], v[118:121], v[50:65]
	v_exp_f32_e32 v104, v104
	v_exp_f32_e32 v105, v105
	v_exp_f32_e32 v106, v106
	ds_read_b64_tr_b16 v[118:119],v130 offset:1024
	ds_read_b64_tr_b16 v[120:121],v130 offset:1536
	s_waitcnt lgkmcnt(14)
	v_mfma_f32_32x32x16_bf16 v[34:49], v[154:157], v[122:125], v[34:49]
	v_exp_f32_e32 v107, v107
	v_exp_f32_e32 v108, v108
	v_exp_f32_e32 v109, v109
	ds_read_b64_tr_b16 v[122:123],v130 offset:2048
	ds_read_b64_tr_b16 v[124:125],v130 offset:2560
	s_waitcnt lgkmcnt(6)
	v_mfma_f32_32x32x16_bf16 v[18:33], v[154:157], v[126:129], v[18:33]
	v_exp_f32_e32 v110, v110
	v_exp_f32_e32 v111, v111
	v_exp_f32_e32 v112, v112
	ds_read_b64_tr_b16 v[126:127],v130 offset:7168
	ds_read_b64_tr_b16 v[128:129],v130 offset:7680
	s_waitcnt lgkmcnt(6)
	v_mfma_f32_32x32x16_bf16 v[18:33], v[166:169], v[114:117], v[18:33]
	v_exp_f32_e32 v113, v113
	v_exp_f32_e32 v82, v82
	v_exp_f32_e32 v83, v83
	ds_read_b64_tr_b16 v[114:115],v130 offset:4096
	ds_read_b64_tr_b16 v[116:117],v130 offset:4608
	s_waitcnt lgkmcnt(6)
	v_mfma_f32_32x32x16_bf16 v[18:33], v[162:165], v[118:121], v[18:33]
	v_exp_f32_e32 v84, v84
	v_exp_f32_e32 v85, v85
	v_exp_f32_e32 v86, v86
	ds_read_b64_tr_b16 v[118:119],v130 offset:5120
	ds_read_b64_tr_b16 v[120:121],v130 offset:5632
	s_waitcnt lgkmcnt(6)
	v_mfma_f32_32x32x16_bf16 v[18:33], v[158:161], v[122:125], v[18:33]
	v_exp_f32_e32 v87, v87
	v_exp_f32_e32 v88, v88
	v_exp_f32_e32 v89, v89
	ds_read_b64_tr_b16 v[122:123],v130 offset:6144
	ds_read_b64_tr_b16 v[124:125],v130 offset:6656
	s_waitcnt lgkmcnt(6)
	v_mfma_f32_32x32x16_bf16 v[2:17], v[154:157], v[126:129], v[2:17]
	v_exp_f32_e32 v90, v90
	v_exp_f32_e32 v91, v91
	s_cmp_lt_u32 s44, 0x1000
	s_cbranch_scc1 .Lstg_lead_3
	s_waitcnt lgkmcnt(0)
	s_andn2_b64 vcc, exec, s[2:3]
	v_mfma_f32_32x32x16_bf16 v[2:17], v[166:169], v[114:117], v[2:17]
	v_exp_f32_e32 v92, v92
	v_exp_f32_e32 v93, v93
	v_mfma_f32_32x32x16_bf16 v[2:17], v[162:165], v[118:121], v[2:17]
	v_exp_f32_e32 v94, v94
	v_exp_f32_e32 v95, v95
	v_mfma_f32_32x32x16_bf16 v[2:17], v[158:161], v[122:125], v[2:17]
	v_exp_f32_e32 v96, v96
	v_exp_f32_e32 v97, v97
	s_waitcnt vmcnt(3)
	s_barrier
	s_branch .Lstg_join_3
.Lstg_lead_3:
	s_waitcnt vmcnt(3) lgkmcnt(0)
	s_barrier
	s_andn2_b64 vcc, exec, s[2:3]
	v_mfma_f32_32x32x16_bf16 v[2:17], v[166:169], v[114:117], v[2:17]
	v_exp_f32_e32 v92, v92
	v_exp_f32_e32 v93, v93
	v_mfma_f32_32x32x16_bf16 v[2:17], v[162:165], v[118:121], v[2:17]
	v_exp_f32_e32 v94, v94
	v_exp_f32_e32 v95, v95
	v_mfma_f32_32x32x16_bf16 v[2:17], v[158:161], v[122:125], v[2:17]
	v_exp_f32_e32 v96, v96
	v_exp_f32_e32 v97, v97
